# v71 + P2 k-norm and compress-task row reductions via DPP (no serial LDS permute round trips)
# baseline (speedup 1.0000x reference)
.LBB0_415:
	s_and_saveexec_b64 s[10:11], s[0:1]
	s_movk_i32 s14, 0xc00
	s_mov_b32 s15, 0
	v_mad_i64_i32 v[10:11], s[16:17], s20, v65, v[44:45]
	global_load_dwordx4 v[12:15], v[10:11], off
	global_load_dwordx4 v[16:19], v[10:11], off offset:1536
	v_lshl_add_u64 v[10:11], v[10:11], 0, s[14:15]
	global_load_dwordx4 v[20:23], v[10:11], off
	global_load_dwordx4 v[24:27], v[10:11], off offset:1536
	v_lshl_add_u64 v[10:11], v[10:11], 0, s[14:15]
	global_load_dwordx4 v[28:31], v[10:11], off
	global_load_dwordx4 v[32:35], v[10:11], off offset:1536
	v_lshl_add_u64 v[10:11], v[10:11], 0, s[14:15]
	global_load_dwordx4 v[36:39], v[10:11], off
	global_load_dwordx4 v[40:43], v[10:11], off offset:1536
	v_lshl_add_u64 v[10:11], v[10:11], 0, s[14:15]
	global_load_dwordx4 v[68:71], v[10:11], off
	global_load_dwordx4 v[72:75], v[10:11], off offset:1536
	v_lshl_add_u64 v[10:11], v[10:11], 0, s[14:15]
	global_load_dwordx4 v[76:79], v[10:11], off
	global_load_dwordx4 v[80:83], v[10:11], off offset:1536
	v_lshl_add_u64 v[10:11], v[10:11], 0, s[14:15]
	global_load_dwordx4 v[84:87], v[10:11], off
	global_load_dwordx4 v[88:91], v[10:11], off offset:1536
	v_lshl_add_u64 v[10:11], v[10:11], 0, s[14:15]
	global_load_dwordx4 v[92:95], v[10:11], off
	global_load_dwordx4 v[96:99], v[10:11], off offset:1536
	v_mad_i64_i32 v[58:59], s[16:17], s20, v65, v[44:45]
	s_waitcnt vmcnt(12)
	v_lshlrev_b32_e32 v100, 16, v12
	v_and_b32_e32 v101, 0xffff0000, v12
	v_lshlrev_b32_e32 v102, 16, v13
	v_and_b32_e32 v103, 0xffff0000, v13
	v_lshlrev_b32_e32 v104, 16, v14
	v_and_b32_e32 v105, 0xffff0000, v14
	v_lshlrev_b32_e32 v106, 16, v15
	v_and_b32_e32 v107, 0xffff0000, v15
	v_pk_mul_f32 v[10:11], v[100:101], v[100:101]
	v_pk_mul_f32 v[126:127], v[102:103], v[102:103]
	v_add_f32_e32 v8, v10, v11
	v_add_f32_e32 v8, v8, v126
	v_add_f32_e32 v8, v8, v127
	v_pk_mul_f32 v[10:11], v[104:105], v[104:105]
	v_pk_mul_f32 v[126:127], v[106:107], v[106:107]
	v_add_f32_e32 v8, v8, v10
	v_add_f32_e32 v8, v8, v11
	v_add_f32_e32 v8, v8, v126
	v_add_f32_e32 v8, v8, v127
	v_lshlrev_b32_e32 v108, 16, v16
	v_and_b32_e32 v109, 0xffff0000, v16
	v_lshlrev_b32_e32 v110, 16, v17
	v_and_b32_e32 v111, 0xffff0000, v17
	v_lshlrev_b32_e32 v112, 16, v18
	v_and_b32_e32 v113, 0xffff0000, v18
	v_lshlrev_b32_e32 v114, 16, v19
	v_and_b32_e32 v115, 0xffff0000, v19
	v_pk_mul_f32 v[10:11], v[108:109], v[108:109]
	v_pk_mul_f32 v[126:127], v[110:111], v[110:111]
	v_add_f32_e32 v54, v10, v11
	v_add_f32_e32 v54, v54, v126
	v_add_f32_e32 v54, v54, v127
	v_pk_mul_f32 v[10:11], v[112:113], v[112:113]
	v_pk_mul_f32 v[126:127], v[114:115], v[114:115]
	v_add_f32_e32 v54, v54, v10
	v_add_f32_e32 v54, v54, v11
	v_add_f32_e32 v54, v54, v126
	v_add_f32_e32 v54, v54, v127
	v_lshlrev_b32_e32 v46, 16, v20
	v_and_b32_e32 v47, 0xffff0000, v20
	v_lshlrev_b32_e32 v48, 16, v21
	v_and_b32_e32 v49, 0xffff0000, v21
	v_lshlrev_b32_e32 v50, 16, v22
	v_and_b32_e32 v51, 0xffff0000, v22
	v_lshlrev_b32_e32 v52, 16, v23
	v_and_b32_e32 v53, 0xffff0000, v23
	v_pk_mul_f32 v[10:11], v[46:47], v[46:47]
	v_pk_mul_f32 v[126:127], v[48:49], v[48:49]
	v_add_f32_e32 v56, v10, v11
	v_add_f32_e32 v56, v56, v126
	v_add_f32_e32 v56, v56, v127
	v_pk_mul_f32 v[10:11], v[50:51], v[50:51]
	v_pk_mul_f32 v[126:127], v[52:53], v[52:53]
	v_add_f32_e32 v56, v56, v10
	v_add_f32_e32 v56, v56, v11
	v_add_f32_e32 v56, v56, v126
	v_add_f32_e32 v56, v56, v127
	v_lshlrev_b32_e32 v116, 16, v24
	v_and_b32_e32 v117, 0xffff0000, v24
	v_lshlrev_b32_e32 v118, 16, v25
	v_and_b32_e32 v119, 0xffff0000, v25
	v_lshlrev_b32_e32 v120, 16, v26
	v_and_b32_e32 v121, 0xffff0000, v26
	v_lshlrev_b32_e32 v122, 16, v27
	v_and_b32_e32 v123, 0xffff0000, v27
	v_pk_mul_f32 v[10:11], v[116:117], v[116:117]
	v_pk_mul_f32 v[126:127], v[118:119], v[118:119]
	v_add_f32_e32 v124, v10, v11
	v_add_f32_e32 v124, v124, v126
	v_add_f32_e32 v124, v124, v127
	v_pk_mul_f32 v[10:11], v[120:121], v[120:121]
	v_pk_mul_f32 v[126:127], v[122:123], v[122:123]
	v_add_f32_e32 v124, v124, v10
	v_add_f32_e32 v124, v124, v11
	v_add_f32_e32 v124, v124, v126
	v_add_f32_e32 v124, v124, v127
	v_add_f32_dpp v8, v8, v8 quad_perm:[1,0,3,2] row_mask:0xf bank_mask:0xf
	v_add_f32_dpp v54, v54, v54 quad_perm:[1,0,3,2] row_mask:0xf bank_mask:0xf
	v_add_f32_dpp v56, v56, v56 quad_perm:[1,0,3,2] row_mask:0xf bank_mask:0xf
	v_add_f32_dpp v124, v124, v124 quad_perm:[1,0,3,2] row_mask:0xf bank_mask:0xf
	v_add_f32_dpp v8, v8, v8 quad_perm:[2,3,0,1] row_mask:0xf bank_mask:0xf
	v_add_f32_dpp v54, v54, v54 quad_perm:[2,3,0,1] row_mask:0xf bank_mask:0xf
	v_add_f32_dpp v56, v56, v56 quad_perm:[2,3,0,1] row_mask:0xf bank_mask:0xf
	v_add_f32_dpp v124, v124, v124 quad_perm:[2,3,0,1] row_mask:0xf bank_mask:0xf
	v_add_f32_dpp v8, v8, v8 row_half_mirror row_mask:0xf bank_mask:0xf
	v_add_f32_dpp v54, v54, v54 row_half_mirror row_mask:0xf bank_mask:0xf
	v_add_f32_dpp v56, v56, v56 row_half_mirror row_mask:0xf bank_mask:0xf
	v_add_f32_dpp v124, v124, v124 row_half_mirror row_mask:0xf bank_mask:0xf
	v_fmamk_f32 v8, v8, 0x3c800000, v64
	v_fmamk_f32 v54, v54, 0x3c800000, v64
	v_fmamk_f32 v56, v56, 0x3c800000, v64
	v_fmamk_f32 v124, v124, 0x3c800000, v64
	v_rsq_f32_e32 v8, v8
	v_rsq_f32_e32 v54, v54
	v_rsq_f32_e32 v56, v56
	v_rsq_f32_e32 v124, v124
	s_nop 0
	v_pk_mul_f32 v[100:101], v[8:9], v[100:101] op_sel_hi:[0,1]
	v_pk_mul_f32 v[102:103], v[8:9], v[102:103] op_sel_hi:[0,1]
	v_pk_mul_f32 v[104:105], v[8:9], v[104:105] op_sel_hi:[0,1]
	v_pk_mul_f32 v[106:107], v[8:9], v[106:107] op_sel_hi:[0,1]
	v_pk_mul_f32 v[100:101], v[4:5], v[100:101]
	v_pk_mul_f32 v[102:103], v[6:7], v[102:103]
	v_pk_mul_f32 v[104:105], v[0:1], v[104:105]
	v_pk_mul_f32 v[106:107], v[2:3], v[106:107]
	v_cvt_pk_bf16_f32 v12, v100, v101
	v_cvt_pk_bf16_f32 v13, v102, v103
	v_cvt_pk_bf16_f32 v14, v104, v105
	v_cvt_pk_bf16_f32 v15, v106, v107
	v_pk_mul_f32 v[108:109], v[54:55], v[108:109] op_sel_hi:[0,1]
	v_pk_mul_f32 v[110:111], v[54:55], v[110:111] op_sel_hi:[0,1]
	v_pk_mul_f32 v[112:113], v[54:55], v[112:113] op_sel_hi:[0,1]
	v_pk_mul_f32 v[114:115], v[54:55], v[114:115] op_sel_hi:[0,1]
	v_pk_mul_f32 v[108:109], v[4:5], v[108:109]
	v_pk_mul_f32 v[110:111], v[6:7], v[110:111]
	v_pk_mul_f32 v[112:113], v[0:1], v[112:113]
	v_pk_mul_f32 v[114:115], v[2:3], v[114:115]
	v_cvt_pk_bf16_f32 v16, v108, v109
	v_cvt_pk_bf16_f32 v17, v110, v111
	v_cvt_pk_bf16_f32 v18, v112, v113
	v_cvt_pk_bf16_f32 v19, v114, v115
	v_pk_mul_f32 v[46:47], v[56:57], v[46:47] op_sel_hi:[0,1]
	v_pk_mul_f32 v[48:49], v[56:57], v[48:49] op_sel_hi:[0,1]
	v_pk_mul_f32 v[50:51], v[56:57], v[50:51] op_sel_hi:[0,1]
	v_pk_mul_f32 v[52:53], v[56:57], v[52:53] op_sel_hi:[0,1]
	v_pk_mul_f32 v[46:47], v[4:5], v[46:47]
	v_pk_mul_f32 v[48:49], v[6:7], v[48:49]
	v_pk_mul_f32 v[50:51], v[0:1], v[50:51]
	v_pk_mul_f32 v[52:53], v[2:3], v[52:53]
	v_cvt_pk_bf16_f32 v20, v46, v47
	v_cvt_pk_bf16_f32 v21, v48, v49
	v_cvt_pk_bf16_f32 v22, v50, v51
	v_cvt_pk_bf16_f32 v23, v52, v53
	v_pk_mul_f32 v[116:117], v[124:125], v[116:117] op_sel_hi:[0,1]
	v_pk_mul_f32 v[118:119], v[124:125], v[118:119] op_sel_hi:[0,1]
	v_pk_mul_f32 v[120:121], v[124:125], v[120:121] op_sel_hi:[0,1]
	v_pk_mul_f32 v[122:123], v[124:125], v[122:123] op_sel_hi:[0,1]
	v_pk_mul_f32 v[116:117], v[4:5], v[116:117]
	v_pk_mul_f32 v[118:119], v[6:7], v[118:119]
	v_pk_mul_f32 v[120:121], v[0:1], v[120:121]
	v_pk_mul_f32 v[122:123], v[2:3], v[122:123]
	v_cvt_pk_bf16_f32 v24, v116, v117
	v_cvt_pk_bf16_f32 v25, v118, v119
	v_cvt_pk_bf16_f32 v26, v120, v121
	v_cvt_pk_bf16_f32 v27, v122, v123
	global_store_dwordx4 v[58:59], v[12:15], off
	global_store_dwordx4 v[58:59], v[16:19], off offset:1536
	global_store_dwordx4 v[58:59], v[20:23], off offset:3072
	v_lshl_add_u64 v[58:59], v[58:59], 0, s[14:15]
	global_store_dwordx4 v[58:59], v[24:27], off offset:1536
	v_lshl_add_u64 v[58:59], v[58:59], 0, s[14:15]
	s_waitcnt vmcnt(12)
	v_lshlrev_b32_e32 v100, 16, v28
	v_and_b32_e32 v101, 0xffff0000, v28
	v_lshlrev_b32_e32 v102, 16, v29
	v_and_b32_e32 v103, 0xffff0000, v29
	v_lshlrev_b32_e32 v104, 16, v30
	v_and_b32_e32 v105, 0xffff0000, v30
	v_lshlrev_b32_e32 v106, 16, v31
	v_and_b32_e32 v107, 0xffff0000, v31
	v_pk_mul_f32 v[10:11], v[100:101], v[100:101]
	v_pk_mul_f32 v[126:127], v[102:103], v[102:103]
	v_add_f32_e32 v8, v10, v11
	v_add_f32_e32 v8, v8, v126
	v_add_f32_e32 v8, v8, v127
	v_pk_mul_f32 v[10:11], v[104:105], v[104:105]
	v_pk_mul_f32 v[126:127], v[106:107], v[106:107]
	v_add_f32_e32 v8, v8, v10
	v_add_f32_e32 v8, v8, v11
	v_add_f32_e32 v8, v8, v126
	v_add_f32_e32 v8, v8, v127
	v_lshlrev_b32_e32 v108, 16, v32
	v_and_b32_e32 v109, 0xffff0000, v32
	v_lshlrev_b32_e32 v110, 16, v33
	v_and_b32_e32 v111, 0xffff0000, v33
	v_lshlrev_b32_e32 v112, 16, v34
	v_and_b32_e32 v113, 0xffff0000, v34
	v_lshlrev_b32_e32 v114, 16, v35
	v_and_b32_e32 v115, 0xffff0000, v35
	v_pk_mul_f32 v[10:11], v[108:109], v[108:109]
	v_pk_mul_f32 v[126:127], v[110:111], v[110:111]
	v_add_f32_e32 v54, v10, v11
	v_add_f32_e32 v54, v54, v126
	v_add_f32_e32 v54, v54, v127
	v_pk_mul_f32 v[10:11], v[112:113], v[112:113]
	v_pk_mul_f32 v[126:127], v[114:115], v[114:115]
	v_add_f32_e32 v54, v54, v10
	v_add_f32_e32 v54, v54, v11
	v_add_f32_e32 v54, v54, v126
	v_add_f32_e32 v54, v54, v127
	v_lshlrev_b32_e32 v46, 16, v36
	v_and_b32_e32 v47, 0xffff0000, v36
	v_lshlrev_b32_e32 v48, 16, v37
	v_and_b32_e32 v49, 0xffff0000, v37
	v_lshlrev_b32_e32 v50, 16, v38
	v_and_b32_e32 v51, 0xffff0000, v38
	v_lshlrev_b32_e32 v52, 16, v39
	v_and_b32_e32 v53, 0xffff0000, v39
	v_pk_mul_f32 v[10:11], v[46:47], v[46:47]
	v_pk_mul_f32 v[126:127], v[48:49], v[48:49]
	v_add_f32_e32 v56, v10, v11
	v_add_f32_e32 v56, v56, v126
	v_add_f32_e32 v56, v56, v127
	v_pk_mul_f32 v[10:11], v[50:51], v[50:51]
	v_pk_mul_f32 v[126:127], v[52:53], v[52:53]
	v_add_f32_e32 v56, v56, v10
	v_add_f32_e32 v56, v56, v11
	v_add_f32_e32 v56, v56, v126
	v_add_f32_e32 v56, v56, v127
	v_lshlrev_b32_e32 v116, 16, v40
	v_and_b32_e32 v117, 0xffff0000, v40
	v_lshlrev_b32_e32 v118, 16, v41
	v_and_b32_e32 v119, 0xffff0000, v41
	v_lshlrev_b32_e32 v120, 16, v42
	v_and_b32_e32 v121, 0xffff0000, v42
	v_lshlrev_b32_e32 v122, 16, v43
	v_and_b32_e32 v123, 0xffff0000, v43
	v_pk_mul_f32 v[10:11], v[116:117], v[116:117]
	v_pk_mul_f32 v[126:127], v[118:119], v[118:119]
	v_add_f32_e32 v124, v10, v11
	v_add_f32_e32 v124, v124, v126
	v_add_f32_e32 v124, v124, v127
	v_pk_mul_f32 v[10:11], v[120:121], v[120:121]
	v_pk_mul_f32 v[126:127], v[122:123], v[122:123]
	v_add_f32_e32 v124, v124, v10
	v_add_f32_e32 v124, v124, v11
	v_add_f32_e32 v124, v124, v126
	v_add_f32_e32 v124, v124, v127
	v_add_f32_dpp v8, v8, v8 quad_perm:[1,0,3,2] row_mask:0xf bank_mask:0xf
	v_add_f32_dpp v54, v54, v54 quad_perm:[1,0,3,2] row_mask:0xf bank_mask:0xf
	v_add_f32_dpp v56, v56, v56 quad_perm:[1,0,3,2] row_mask:0xf bank_mask:0xf
	v_add_f32_dpp v124, v124, v124 quad_perm:[1,0,3,2] row_mask:0xf bank_mask:0xf
	v_add_f32_dpp v8, v8, v8 quad_perm:[2,3,0,1] row_mask:0xf bank_mask:0xf
	v_add_f32_dpp v54, v54, v54 quad_perm:[2,3,0,1] row_mask:0xf bank_mask:0xf
	v_add_f32_dpp v56, v56, v56 quad_perm:[2,3,0,1] row_mask:0xf bank_mask:0xf
	v_add_f32_dpp v124, v124, v124 quad_perm:[2,3,0,1] row_mask:0xf bank_mask:0xf
	v_add_f32_dpp v8, v8, v8 row_half_mirror row_mask:0xf bank_mask:0xf
	v_add_f32_dpp v54, v54, v54 row_half_mirror row_mask:0xf bank_mask:0xf
	v_add_f32_dpp v56, v56, v56 row_half_mirror row_mask:0xf bank_mask:0xf
	v_add_f32_dpp v124, v124, v124 row_half_mirror row_mask:0xf bank_mask:0xf
	v_fmamk_f32 v8, v8, 0x3c800000, v64
	v_fmamk_f32 v54, v54, 0x3c800000, v64
	v_fmamk_f32 v56, v56, 0x3c800000, v64
	v_fmamk_f32 v124, v124, 0x3c800000, v64
	v_rsq_f32_e32 v8, v8
	v_rsq_f32_e32 v54, v54
	v_rsq_f32_e32 v56, v56
	v_rsq_f32_e32 v124, v124
	s_nop 0
	v_pk_mul_f32 v[100:101], v[8:9], v[100:101] op_sel_hi:[0,1]
	v_pk_mul_f32 v[102:103], v[8:9], v[102:103] op_sel_hi:[0,1]
	v_pk_mul_f32 v[104:105], v[8:9], v[104:105] op_sel_hi:[0,1]
	v_pk_mul_f32 v[106:107], v[8:9], v[106:107] op_sel_hi:[0,1]
	v_pk_mul_f32 v[100:101], v[4:5], v[100:101]
	v_pk_mul_f32 v[102:103], v[6:7], v[102:103]
	v_pk_mul_f32 v[104:105], v[0:1], v[104:105]
	v_pk_mul_f32 v[106:107], v[2:3], v[106:107]
	v_cvt_pk_bf16_f32 v28, v100, v101
	v_cvt_pk_bf16_f32 v29, v102, v103
	v_cvt_pk_bf16_f32 v30, v104, v105
	v_cvt_pk_bf16_f32 v31, v106, v107
	v_pk_mul_f32 v[108:109], v[54:55], v[108:109] op_sel_hi:[0,1]
	v_pk_mul_f32 v[110:111], v[54:55], v[110:111] op_sel_hi:[0,1]
	v_pk_mul_f32 v[112:113], v[54:55], v[112:113] op_sel_hi:[0,1]
	v_pk_mul_f32 v[114:115], v[54:55], v[114:115] op_sel_hi:[0,1]
	v_pk_mul_f32 v[108:109], v[4:5], v[108:109]
	v_pk_mul_f32 v[110:111], v[6:7], v[110:111]
	v_pk_mul_f32 v[112:113], v[0:1], v[112:113]
	v_pk_mul_f32 v[114:115], v[2:3], v[114:115]
	v_cvt_pk_bf16_f32 v32, v108, v109
	v_cvt_pk_bf16_f32 v33, v110, v111
	v_cvt_pk_bf16_f32 v34, v112, v113
	v_cvt_pk_bf16_f32 v35, v114, v115
	v_pk_mul_f32 v[46:47], v[56:57], v[46:47] op_sel_hi:[0,1]
	v_pk_mul_f32 v[48:49], v[56:57], v[48:49] op_sel_hi:[0,1]
	v_pk_mul_f32 v[50:51], v[56:57], v[50:51] op_sel_hi:[0,1]
	v_pk_mul_f32 v[52:53], v[56:57], v[52:53] op_sel_hi:[0,1]
	v_pk_mul_f32 v[46:47], v[4:5], v[46:47]
	v_pk_mul_f32 v[48:49], v[6:7], v[48:49]
	v_pk_mul_f32 v[50:51], v[0:1], v[50:51]
	v_pk_mul_f32 v[52:53], v[2:3], v[52:53]
	v_cvt_pk_bf16_f32 v36, v46, v47
	v_cvt_pk_bf16_f32 v37, v48, v49
	v_cvt_pk_bf16_f32 v38, v50, v51
	v_cvt_pk_bf16_f32 v39, v52, v53
	v_pk_mul_f32 v[116:117], v[124:125], v[116:117] op_sel_hi:[0,1]
	v_pk_mul_f32 v[118:119], v[124:125], v[118:119] op_sel_hi:[0,1]
	v_pk_mul_f32 v[120:121], v[124:125], v[120:121] op_sel_hi:[0,1]
	v_pk_mul_f32 v[122:123], v[124:125], v[122:123] op_sel_hi:[0,1]
	v_pk_mul_f32 v[116:117], v[4:5], v[116:117]
	v_pk_mul_f32 v[118:119], v[6:7], v[118:119]
	v_pk_mul_f32 v[120:121], v[0:1], v[120:121]
	v_pk_mul_f32 v[122:123], v[2:3], v[122:123]
	v_cvt_pk_bf16_f32 v40, v116, v117
	v_cvt_pk_bf16_f32 v41, v118, v119
	v_cvt_pk_bf16_f32 v42, v120, v121
	v_cvt_pk_bf16_f32 v43, v122, v123
	global_store_dwordx4 v[58:59], v[28:31], off
	global_store_dwordx4 v[58:59], v[32:35], off offset:1536
	global_store_dwordx4 v[58:59], v[36:39], off offset:3072
	v_lshl_add_u64 v[58:59], v[58:59], 0, s[14:15]
	global_store_dwordx4 v[58:59], v[40:43], off offset:1536
	v_lshl_add_u64 v[58:59], v[58:59], 0, s[14:15]
	s_waitcnt vmcnt(12)
	v_lshlrev_b32_e32 v100, 16, v68
	v_and_b32_e32 v101, 0xffff0000, v68
	v_lshlrev_b32_e32 v102, 16, v69
	v_and_b32_e32 v103, 0xffff0000, v69
	v_lshlrev_b32_e32 v104, 16, v70
	v_and_b32_e32 v105, 0xffff0000, v70
	v_lshlrev_b32_e32 v106, 16, v71
	v_and_b32_e32 v107, 0xffff0000, v71
	v_pk_mul_f32 v[10:11], v[100:101], v[100:101]
	v_pk_mul_f32 v[126:127], v[102:103], v[102:103]
	v_add_f32_e32 v8, v10, v11
	v_add_f32_e32 v8, v8, v126
	v_add_f32_e32 v8, v8, v127
	v_pk_mul_f32 v[10:11], v[104:105], v[104:105]
	v_pk_mul_f32 v[126:127], v[106:107], v[106:107]
	v_add_f32_e32 v8, v8, v10
	v_add_f32_e32 v8, v8, v11
	v_add_f32_e32 v8, v8, v126
	v_add_f32_e32 v8, v8, v127
	v_lshlrev_b32_e32 v108, 16, v72
	v_and_b32_e32 v109, 0xffff0000, v72
	v_lshlrev_b32_e32 v110, 16, v73
	v_and_b32_e32 v111, 0xffff0000, v73
	v_lshlrev_b32_e32 v112, 16, v74
	v_and_b32_e32 v113, 0xffff0000, v74
	v_lshlrev_b32_e32 v114, 16, v75
	v_and_b32_e32 v115, 0xffff0000, v75
	v_pk_mul_f32 v[10:11], v[108:109], v[108:109]
	v_pk_mul_f32 v[126:127], v[110:111], v[110:111]
	v_add_f32_e32 v54, v10, v11
	v_add_f32_e32 v54, v54, v126
	v_add_f32_e32 v54, v54, v127
	v_pk_mul_f32 v[10:11], v[112:113], v[112:113]
	v_pk_mul_f32 v[126:127], v[114:115], v[114:115]
	v_add_f32_e32 v54, v54, v10
	v_add_f32_e32 v54, v54, v11
	v_add_f32_e32 v54, v54, v126
	v_add_f32_e32 v54, v54, v127
	v_lshlrev_b32_e32 v46, 16, v76
	v_and_b32_e32 v47, 0xffff0000, v76
	v_lshlrev_b32_e32 v48, 16, v77
	v_and_b32_e32 v49, 0xffff0000, v77
	v_lshlrev_b32_e32 v50, 16, v78
	v_and_b32_e32 v51, 0xffff0000, v78
	v_lshlrev_b32_e32 v52, 16, v79
	v_and_b32_e32 v53, 0xffff0000, v79
	v_pk_mul_f32 v[10:11], v[46:47], v[46:47]
	v_pk_mul_f32 v[126:127], v[48:49], v[48:49]
	v_add_f32_e32 v56, v10, v11
	v_add_f32_e32 v56, v56, v126
	v_add_f32_e32 v56, v56, v127
	v_pk_mul_f32 v[10:11], v[50:51], v[50:51]
	v_pk_mul_f32 v[126:127], v[52:53], v[52:53]
	v_add_f32_e32 v56, v56, v10
	v_add_f32_e32 v56, v56, v11
	v_add_f32_e32 v56, v56, v126
	v_add_f32_e32 v56, v56, v127
	v_lshlrev_b32_e32 v116, 16, v80
	v_and_b32_e32 v117, 0xffff0000, v80
	v_lshlrev_b32_e32 v118, 16, v81
	v_and_b32_e32 v119, 0xffff0000, v81
	v_lshlrev_b32_e32 v120, 16, v82
	v_and_b32_e32 v121, 0xffff0000, v82
	v_lshlrev_b32_e32 v122, 16, v83
	v_and_b32_e32 v123, 0xffff0000, v83
	v_pk_mul_f32 v[10:11], v[116:117], v[116:117]
	v_pk_mul_f32 v[126:127], v[118:119], v[118:119]
	v_add_f32_e32 v124, v10, v11
	v_add_f32_e32 v124, v124, v126
	v_add_f32_e32 v124, v124, v127
	v_pk_mul_f32 v[10:11], v[120:121], v[120:121]
	v_pk_mul_f32 v[126:127], v[122:123], v[122:123]
	v_add_f32_e32 v124, v124, v10
	v_add_f32_e32 v124, v124, v11
	v_add_f32_e32 v124, v124, v126
	v_add_f32_e32 v124, v124, v127
	v_add_f32_dpp v8, v8, v8 quad_perm:[1,0,3,2] row_mask:0xf bank_mask:0xf
	v_add_f32_dpp v54, v54, v54 quad_perm:[1,0,3,2] row_mask:0xf bank_mask:0xf
	v_add_f32_dpp v56, v56, v56 quad_perm:[1,0,3,2] row_mask:0xf bank_mask:0xf
	v_add_f32_dpp v124, v124, v124 quad_perm:[1,0,3,2] row_mask:0xf bank_mask:0xf
	v_add_f32_dpp v8, v8, v8 quad_perm:[2,3,0,1] row_mask:0xf bank_mask:0xf
	v_add_f32_dpp v54, v54, v54 quad_perm:[2,3,0,1] row_mask:0xf bank_mask:0xf
	v_add_f32_dpp v56, v56, v56 quad_perm:[2,3,0,1] row_mask:0xf bank_mask:0xf
	v_add_f32_dpp v124, v124, v124 quad_perm:[2,3,0,1] row_mask:0xf bank_mask:0xf
	v_add_f32_dpp v8, v8, v8 row_half_mirror row_mask:0xf bank_mask:0xf
	v_add_f32_dpp v54, v54, v54 row_half_mirror row_mask:0xf bank_mask:0xf
	v_add_f32_dpp v56, v56, v56 row_half_mirror row_mask:0xf bank_mask:0xf
	v_add_f32_dpp v124, v124, v124 row_half_mirror row_mask:0xf bank_mask:0xf
	v_fmamk_f32 v8, v8, 0x3c800000, v64
	v_fmamk_f32 v54, v54, 0x3c800000, v64
	v_fmamk_f32 v56, v56, 0x3c800000, v64
	v_fmamk_f32 v124, v124, 0x3c800000, v64
	v_rsq_f32_e32 v8, v8
	v_rsq_f32_e32 v54, v54
	v_rsq_f32_e32 v56, v56
	v_rsq_f32_e32 v124, v124
	s_nop 0
	v_pk_mul_f32 v[100:101], v[8:9], v[100:101] op_sel_hi:[0,1]
	v_pk_mul_f32 v[102:103], v[8:9], v[102:103] op_sel_hi:[0,1]
	v_pk_mul_f32 v[104:105], v[8:9], v[104:105] op_sel_hi:[0,1]
	v_pk_mul_f32 v[106:107], v[8:9], v[106:107] op_sel_hi:[0,1]
	v_pk_mul_f32 v[100:101], v[4:5], v[100:101]
	v_pk_mul_f32 v[102:103], v[6:7], v[102:103]
	v_pk_mul_f32 v[104:105], v[0:1], v[104:105]
	v_pk_mul_f32 v[106:107], v[2:3], v[106:107]
	v_cvt_pk_bf16_f32 v68, v100, v101
	v_cvt_pk_bf16_f32 v69, v102, v103
	v_cvt_pk_bf16_f32 v70, v104, v105
	v_cvt_pk_bf16_f32 v71, v106, v107
	v_pk_mul_f32 v[108:109], v[54:55], v[108:109] op_sel_hi:[0,1]
	v_pk_mul_f32 v[110:111], v[54:55], v[110:111] op_sel_hi:[0,1]
	v_pk_mul_f32 v[112:113], v[54:55], v[112:113] op_sel_hi:[0,1]
	v_pk_mul_f32 v[114:115], v[54:55], v[114:115] op_sel_hi:[0,1]
	v_pk_mul_f32 v[108:109], v[4:5], v[108:109]
	v_pk_mul_f32 v[110:111], v[6:7], v[110:111]
	v_pk_mul_f32 v[112:113], v[0:1], v[112:113]
	v_pk_mul_f32 v[114:115], v[2:3], v[114:115]
	v_cvt_pk_bf16_f32 v72, v108, v109
	v_cvt_pk_bf16_f32 v73, v110, v111
	v_cvt_pk_bf16_f32 v74, v112, v113
	v_cvt_pk_bf16_f32 v75, v114, v115
	v_pk_mul_f32 v[46:47], v[56:57], v[46:47] op_sel_hi:[0,1]
	v_pk_mul_f32 v[48:49], v[56:57], v[48:49] op_sel_hi:[0,1]
	v_pk_mul_f32 v[50:51], v[56:57], v[50:51] op_sel_hi:[0,1]
	v_pk_mul_f32 v[52:53], v[56:57], v[52:53] op_sel_hi:[0,1]
	v_pk_mul_f32 v[46:47], v[4:5], v[46:47]
	v_pk_mul_f32 v[48:49], v[6:7], v[48:49]
	v_pk_mul_f32 v[50:51], v[0:1], v[50:51]
	v_pk_mul_f32 v[52:53], v[2:3], v[52:53]
	v_cvt_pk_bf16_f32 v76, v46, v47
	v_cvt_pk_bf16_f32 v77, v48, v49
	v_cvt_pk_bf16_f32 v78, v50, v51
	v_cvt_pk_bf16_f32 v79, v52, v53
	v_pk_mul_f32 v[116:117], v[124:125], v[116:117] op_sel_hi:[0,1]
	v_pk_mul_f32 v[118:119], v[124:125], v[118:119] op_sel_hi:[0,1]
	v_pk_mul_f32 v[120:121], v[124:125], v[120:121] op_sel_hi:[0,1]
	v_pk_mul_f32 v[122:123], v[124:125], v[122:123] op_sel_hi:[0,1]
	v_pk_mul_f32 v[116:117], v[4:5], v[116:117]
	v_pk_mul_f32 v[118:119], v[6:7], v[118:119]
	v_pk_mul_f32 v[120:121], v[0:1], v[120:121]
	v_pk_mul_f32 v[122:123], v[2:3], v[122:123]
	v_cvt_pk_bf16_f32 v80, v116, v117
	v_cvt_pk_bf16_f32 v81, v118, v119
	v_cvt_pk_bf16_f32 v82, v120, v121
	v_cvt_pk_bf16_f32 v83, v122, v123
	global_store_dwordx4 v[58:59], v[68:71], off
	global_store_dwordx4 v[58:59], v[72:75], off offset:1536
	global_store_dwordx4 v[58:59], v[76:79], off offset:3072
	v_lshl_add_u64 v[58:59], v[58:59], 0, s[14:15]
	global_store_dwordx4 v[58:59], v[80:83], off offset:1536
	v_lshl_add_u64 v[58:59], v[58:59], 0, s[14:15]
	s_waitcnt vmcnt(12)
	v_lshlrev_b32_e32 v100, 16, v84
	v_and_b32_e32 v101, 0xffff0000, v84
	v_lshlrev_b32_e32 v102, 16, v85
	v_and_b32_e32 v103, 0xffff0000, v85
	v_lshlrev_b32_e32 v104, 16, v86
	v_and_b32_e32 v105, 0xffff0000, v86
	v_lshlrev_b32_e32 v106, 16, v87
	v_and_b32_e32 v107, 0xffff0000, v87
	v_pk_mul_f32 v[10:11], v[100:101], v[100:101]
	v_pk_mul_f32 v[126:127], v[102:103], v[102:103]
	v_add_f32_e32 v8, v10, v11
	v_add_f32_e32 v8, v8, v126
	v_add_f32_e32 v8, v8, v127
	v_pk_mul_f32 v[10:11], v[104:105], v[104:105]
	v_pk_mul_f32 v[126:127], v[106:107], v[106:107]
	v_add_f32_e32 v8, v8, v10
	v_add_f32_e32 v8, v8, v11
	v_add_f32_e32 v8, v8, v126
	v_add_f32_e32 v8, v8, v127
	v_lshlrev_b32_e32 v108, 16, v88
	v_and_b32_e32 v109, 0xffff0000, v88
	v_lshlrev_b32_e32 v110, 16, v89
	v_and_b32_e32 v111, 0xffff0000, v89
	v_lshlrev_b32_e32 v112, 16, v90
	v_and_b32_e32 v113, 0xffff0000, v90
	v_lshlrev_b32_e32 v114, 16, v91
	v_and_b32_e32 v115, 0xffff0000, v91
	v_pk_mul_f32 v[10:11], v[108:109], v[108:109]
	v_pk_mul_f32 v[126:127], v[110:111], v[110:111]
	v_add_f32_e32 v54, v10, v11
	v_add_f32_e32 v54, v54, v126
	v_add_f32_e32 v54, v54, v127
	v_pk_mul_f32 v[10:11], v[112:113], v[112:113]
	v_pk_mul_f32 v[126:127], v[114:115], v[114:115]
	v_add_f32_e32 v54, v54, v10
	v_add_f32_e32 v54, v54, v11
	v_add_f32_e32 v54, v54, v126
	v_add_f32_e32 v54, v54, v127
	v_lshlrev_b32_e32 v46, 16, v92
	v_and_b32_e32 v47, 0xffff0000, v92
	v_lshlrev_b32_e32 v48, 16, v93
	v_and_b32_e32 v49, 0xffff0000, v93
	v_lshlrev_b32_e32 v50, 16, v94
	v_and_b32_e32 v51, 0xffff0000, v94
	v_lshlrev_b32_e32 v52, 16, v95
	v_and_b32_e32 v53, 0xffff0000, v95
	v_pk_mul_f32 v[10:11], v[46:47], v[46:47]
	v_pk_mul_f32 v[126:127], v[48:49], v[48:49]
	v_add_f32_e32 v56, v10, v11
	v_add_f32_e32 v56, v56, v126
	v_add_f32_e32 v56, v56, v127
	v_pk_mul_f32 v[10:11], v[50:51], v[50:51]
	v_pk_mul_f32 v[126:127], v[52:53], v[52:53]
	v_add_f32_e32 v56, v56, v10
	v_add_f32_e32 v56, v56, v11
	v_add_f32_e32 v56, v56, v126
	v_add_f32_e32 v56, v56, v127
	v_lshlrev_b32_e32 v116, 16, v96
	v_and_b32_e32 v117, 0xffff0000, v96
	v_lshlrev_b32_e32 v118, 16, v97
	v_and_b32_e32 v119, 0xffff0000, v97
	v_lshlrev_b32_e32 v120, 16, v98
	v_and_b32_e32 v121, 0xffff0000, v98
	v_lshlrev_b32_e32 v122, 16, v99
	v_and_b32_e32 v123, 0xffff0000, v99
	v_pk_mul_f32 v[10:11], v[116:117], v[116:117]
	v_pk_mul_f32 v[126:127], v[118:119], v[118:119]
	v_add_f32_e32 v124, v10, v11
	v_add_f32_e32 v124, v124, v126
	v_add_f32_e32 v124, v124, v127
	v_pk_mul_f32 v[10:11], v[120:121], v[120:121]
	v_pk_mul_f32 v[126:127], v[122:123], v[122:123]
	v_add_f32_e32 v124, v124, v10
	v_add_f32_e32 v124, v124, v11
	v_add_f32_e32 v124, v124, v126
	v_add_f32_e32 v124, v124, v127
	v_add_f32_dpp v8, v8, v8 quad_perm:[1,0,3,2] row_mask:0xf bank_mask:0xf
	v_add_f32_dpp v54, v54, v54 quad_perm:[1,0,3,2] row_mask:0xf bank_mask:0xf
	v_add_f32_dpp v56, v56, v56 quad_perm:[1,0,3,2] row_mask:0xf bank_mask:0xf
	v_add_f32_dpp v124, v124, v124 quad_perm:[1,0,3,2] row_mask:0xf bank_mask:0xf
	v_add_f32_dpp v8, v8, v8 quad_perm:[2,3,0,1] row_mask:0xf bank_mask:0xf
	v_add_f32_dpp v54, v54, v54 quad_perm:[2,3,0,1] row_mask:0xf bank_mask:0xf
	v_add_f32_dpp v56, v56, v56 quad_perm:[2,3,0,1] row_mask:0xf bank_mask:0xf
	v_add_f32_dpp v124, v124, v124 quad_perm:[2,3,0,1] row_mask:0xf bank_mask:0xf
	v_add_f32_dpp v8, v8, v8 row_half_mirror row_mask:0xf bank_mask:0xf
	v_add_f32_dpp v54, v54, v54 row_half_mirror row_mask:0xf bank_mask:0xf
	v_add_f32_dpp v56, v56, v56 row_half_mirror row_mask:0xf bank_mask:0xf
	v_add_f32_dpp v124, v124, v124 row_half_mirror row_mask:0xf bank_mask:0xf
	v_fmamk_f32 v8, v8, 0x3c800000, v64
	v_fmamk_f32 v54, v54, 0x3c800000, v64
	v_fmamk_f32 v56, v56, 0x3c800000, v64
	v_fmamk_f32 v124, v124, 0x3c800000, v64
	v_rsq_f32_e32 v8, v8
	v_rsq_f32_e32 v54, v54
	v_rsq_f32_e32 v56, v56
	v_rsq_f32_e32 v124, v124
	s_nop 0
	v_pk_mul_f32 v[100:101], v[8:9], v[100:101] op_sel_hi:[0,1]
	v_pk_mul_f32 v[102:103], v[8:9], v[102:103] op_sel_hi:[0,1]
	v_pk_mul_f32 v[104:105], v[8:9], v[104:105] op_sel_hi:[0,1]
	v_pk_mul_f32 v[106:107], v[8:9], v[106:107] op_sel_hi:[0,1]
	v_pk_mul_f32 v[100:101], v[4:5], v[100:101]
	v_pk_mul_f32 v[102:103], v[6:7], v[102:103]
	v_pk_mul_f32 v[104:105], v[0:1], v[104:105]
	v_pk_mul_f32 v[106:107], v[2:3], v[106:107]
	v_cvt_pk_bf16_f32 v84, v100, v101
	v_cvt_pk_bf16_f32 v85, v102, v103
	v_cvt_pk_bf16_f32 v86, v104, v105
	v_cvt_pk_bf16_f32 v87, v106, v107
	v_pk_mul_f32 v[108:109], v[54:55], v[108:109] op_sel_hi:[0,1]
	v_pk_mul_f32 v[110:111], v[54:55], v[110:111] op_sel_hi:[0,1]
	v_pk_mul_f32 v[112:113], v[54:55], v[112:113] op_sel_hi:[0,1]
	v_pk_mul_f32 v[114:115], v[54:55], v[114:115] op_sel_hi:[0,1]
	v_pk_mul_f32 v[108:109], v[4:5], v[108:109]
	v_pk_mul_f32 v[110:111], v[6:7], v[110:111]
	v_pk_mul_f32 v[112:113], v[0:1], v[112:113]
	v_pk_mul_f32 v[114:115], v[2:3], v[114:115]
	v_cvt_pk_bf16_f32 v88, v108, v109
	v_cvt_pk_bf16_f32 v89, v110, v111
	v_cvt_pk_bf16_f32 v90, v112, v113
	v_cvt_pk_bf16_f32 v91, v114, v115
	v_pk_mul_f32 v[46:47], v[56:57], v[46:47] op_sel_hi:[0,1]
	v_pk_mul_f32 v[48:49], v[56:57], v[48:49] op_sel_hi:[0,1]
	v_pk_mul_f32 v[50:51], v[56:57], v[50:51] op_sel_hi:[0,1]
	v_pk_mul_f32 v[52:53], v[56:57], v[52:53] op_sel_hi:[0,1]
	v_pk_mul_f32 v[46:47], v[4:5], v[46:47]
	v_pk_mul_f32 v[48:49], v[6:7], v[48:49]
	v_pk_mul_f32 v[50:51], v[0:1], v[50:51]
	v_pk_mul_f32 v[52:53], v[2:3], v[52:53]
	v_cvt_pk_bf16_f32 v92, v46, v47
	v_cvt_pk_bf16_f32 v93, v48, v49
	v_cvt_pk_bf16_f32 v94, v50, v51
	v_cvt_pk_bf16_f32 v95, v52, v53
	v_pk_mul_f32 v[116:117], v[124:125], v[116:117] op_sel_hi:[0,1]
	v_pk_mul_f32 v[118:119], v[124:125], v[118:119] op_sel_hi:[0,1]
	v_pk_mul_f32 v[120:121], v[124:125], v[120:121] op_sel_hi:[0,1]
	v_pk_mul_f32 v[122:123], v[124:125], v[122:123] op_sel_hi:[0,1]
	v_pk_mul_f32 v[116:117], v[4:5], v[116:117]
	v_pk_mul_f32 v[118:119], v[6:7], v[118:119]
	v_pk_mul_f32 v[120:121], v[0:1], v[120:121]
	v_pk_mul_f32 v[122:123], v[2:3], v[122:123]
	v_cvt_pk_bf16_f32 v96, v116, v117
	v_cvt_pk_bf16_f32 v97, v118, v119
	v_cvt_pk_bf16_f32 v98, v120, v121
	v_cvt_pk_bf16_f32 v99, v122, v123
	global_store_dwordx4 v[58:59], v[84:87], off
	global_store_dwordx4 v[58:59], v[88:91], off offset:1536
	global_store_dwordx4 v[58:59], v[92:95], off offset:3072
	v_lshl_add_u64 v[58:59], v[58:59], 0, s[14:15]
	global_store_dwordx4 v[58:59], v[96:99], off offset:1536
	s_or_b64 exec, exec, s[10:11]
	s_branch .LBB0_433

.LBB0_446:
	s_andn2_b64 vcc, exec, s[72:73]
	s_cbranch_vccnz .LBB0_443
	v_pk_mul_f32 v[6:7], v[0:1], v[0:1]
	v_pk_mul_f32 v[8:9], v[2:3], v[2:3]
	s_nop 0
	v_pk_mov_b32 v[10:11], v[8:9], v[6:7] op_sel:[1,0]
	v_mov_b32_e32 v9, v7
	v_pk_add_f32 v[6:7], v[10:11], v[8:9]
	v_and_b32_e32 v8, 64, v70
	v_add_f32_e32 v6, v6, v7
	s_nop 1
	v_add_f32_dpp v6, v6, v6 quad_perm:[1,0,3,2] row_mask:0xf bank_mask:0xf
	s_nop 1
	v_add_f32_dpp v6, v6, v6 quad_perm:[2,3,0,1] row_mask:0xf bank_mask:0xf
	s_nop 1
	v_add_f32_dpp v6, v6, v6 row_half_mirror row_mask:0xf bank_mask:0xf
	s_nop 1
	v_add_f32_dpp v6, v6, v6 row_mirror row_mask:0xf bank_mask:0xf
	v_fmamk_f32 v6, v6, 0x3c800000, v66
	v_rsq_f32_e32 v10, v6
	global_load_dwordx4 v[6:9], v[40:41], off
	v_pk_mul_f32 v[2:3], v[2:3], v[10:11] op_sel_hi:[1,0]
	v_pk_mul_f32 v[0:1], v[0:1], v[10:11] op_sel_hi:[1,0]
	s_waitcnt vmcnt(0)
	v_pk_mul_f32 v[2:3], v[6:7], v[2:3]
	v_pk_mul_f32 v[0:1], v[8:9], v[0:1]
	v_cvt_pk_bf16_f32 v2, v2, v3
	v_cvt_pk_bf16_f32 v3, v0, v1
	v_and_b32_e32 v0, 0x1e00, v4
	v_or3_b32 v0, v0, v63, v5
	v_lshlrev_b32_e32 v36, 7, v0
	v_lshl_add_u64 v[0:1], v[42:43], 0, v[36:37]
	global_store_dwordx2 v[0:1], v[2:3], off
	s_branch .LBB0_443
